# plus per-tile M3->M4 hand-off counters (no global wait for all merge tiles before the RWKV quarter)
# speedup vs baseline: 1.0136x; 1.0029x over previous
.LBB0_1071:
	s_andn2_b64 vcc, exec, s[30:31]
	s_mov_b64 s[30:31], 0
	s_cbranch_vccnz .LBB0_1075
	v_lshlrev_b32_e32 v146, 16, v50
	v_and_b32_e32 v147, 0xffff0000, v50
	v_lshlrev_b32_e32 v148, 16, v224
	v_and_b32_e32 v149, 0xffff0000, v224
	v_pk_fma_f32 v[142:143], v[142:143], v[148:149], v[146:147]
	v_lshlrev_b32_e32 v50, 16, v51
	v_and_b32_e32 v51, 0xffff0000, v51
	v_lshlrev_b32_e32 v146, 16, v225
	v_and_b32_e32 v147, 0xffff0000, v225
	v_pk_fma_f32 v[144:145], v[144:145], v[146:147], v[50:51]
	v_cvt_pk_bf16_f32 v50, v142, v143
	v_cvt_pk_bf16_f32 v51, v144, v145
	v_lshlrev_b32_e32 v142, 16, v52
	v_and_b32_e32 v143, 0xffff0000, v52
	v_lshlrev_b32_e32 v144, 16, v222
	v_and_b32_e32 v145, 0xffff0000, v222
	v_pk_fma_f32 v[138:139], v[138:139], v[144:145], v[142:143]
	v_lshlrev_b32_e32 v52, 16, v53
	v_and_b32_e32 v53, 0xffff0000, v53
	v_lshlrev_b32_e32 v142, 16, v223
	v_and_b32_e32 v143, 0xffff0000, v223
	v_pk_fma_f32 v[140:141], v[140:141], v[142:143], v[52:53]
	v_cvt_pk_bf16_f32 v52, v138, v139
	v_cvt_pk_bf16_f32 v53, v140, v141
	v_lshlrev_b32_e32 v138, 16, v78
	v_and_b32_e32 v139, 0xffff0000, v78
	v_lshlrev_b32_e32 v140, 16, v220
	v_and_b32_e32 v141, 0xffff0000, v220
	v_pk_fma_f32 v[134:135], v[134:135], v[140:141], v[138:139]
	v_lshlrev_b32_e32 v78, 16, v79
	v_and_b32_e32 v79, 0xffff0000, v79
	v_lshlrev_b32_e32 v138, 16, v221
	v_and_b32_e32 v139, 0xffff0000, v221
	v_pk_fma_f32 v[136:137], v[136:137], v[138:139], v[78:79]
	v_cvt_pk_bf16_f32 v78, v134, v135
	v_cvt_pk_bf16_f32 v79, v136, v137
	v_lshlrev_b32_e32 v134, 16, v80
	v_and_b32_e32 v135, 0xffff0000, v80
	v_lshlrev_b32_e32 v136, 16, v218
	v_and_b32_e32 v137, 0xffff0000, v218
	v_pk_fma_f32 v[130:131], v[130:131], v[136:137], v[134:135]
	v_lshlrev_b32_e32 v80, 16, v81
	v_and_b32_e32 v81, 0xffff0000, v81
	v_lshlrev_b32_e32 v134, 16, v219
	v_and_b32_e32 v135, 0xffff0000, v219
	v_pk_fma_f32 v[132:133], v[132:133], v[134:135], v[80:81]
	v_cvt_pk_bf16_f32 v80, v130, v131
	v_cvt_pk_bf16_f32 v81, v132, v133
	v_lshlrev_b32_e32 v130, 16, v74
	v_and_b32_e32 v131, 0xffff0000, v74
	v_lshlrev_b32_e32 v132, 16, v216
	v_and_b32_e32 v133, 0xffff0000, v216
	v_pk_fma_f32 v[126:127], v[126:127], v[132:133], v[130:131]
	v_lshlrev_b32_e32 v74, 16, v75
	v_and_b32_e32 v75, 0xffff0000, v75
	v_lshlrev_b32_e32 v130, 16, v217
	v_and_b32_e32 v131, 0xffff0000, v217
	v_pk_fma_f32 v[128:129], v[128:129], v[130:131], v[74:75]
	v_cvt_pk_bf16_f32 v74, v126, v127
	v_cvt_pk_bf16_f32 v75, v128, v129
	v_lshlrev_b32_e32 v126, 16, v76
	v_and_b32_e32 v127, 0xffff0000, v76
	v_lshlrev_b32_e32 v128, 16, v214
	v_and_b32_e32 v129, 0xffff0000, v214
	v_pk_fma_f32 v[122:123], v[122:123], v[128:129], v[126:127]
	v_lshlrev_b32_e32 v76, 16, v77
	v_and_b32_e32 v77, 0xffff0000, v77
	v_lshlrev_b32_e32 v126, 16, v215
	v_and_b32_e32 v127, 0xffff0000, v215
	v_pk_fma_f32 v[124:125], v[124:125], v[126:127], v[76:77]
	v_cvt_pk_bf16_f32 v76, v122, v123
	v_cvt_pk_bf16_f32 v77, v124, v125
	v_lshlrev_b32_e32 v122, 16, v70
	v_and_b32_e32 v123, 0xffff0000, v70
	v_lshlrev_b32_e32 v124, 16, v212
	v_and_b32_e32 v125, 0xffff0000, v212
	v_pk_fma_f32 v[118:119], v[118:119], v[124:125], v[122:123]
	v_lshlrev_b32_e32 v70, 16, v71
	v_and_b32_e32 v71, 0xffff0000, v71
	v_lshlrev_b32_e32 v122, 16, v213
	v_and_b32_e32 v123, 0xffff0000, v213
	v_pk_fma_f32 v[120:121], v[120:121], v[122:123], v[70:71]
	v_cvt_pk_bf16_f32 v70, v118, v119
	v_cvt_pk_bf16_f32 v71, v120, v121
	v_lshlrev_b32_e32 v118, 16, v72
	v_and_b32_e32 v119, 0xffff0000, v72
	v_lshlrev_b32_e32 v120, 16, v210
	v_and_b32_e32 v121, 0xffff0000, v210
	v_pk_fma_f32 v[114:115], v[114:115], v[120:121], v[118:119]
	v_lshlrev_b32_e32 v72, 16, v73
	v_and_b32_e32 v73, 0xffff0000, v73
	v_lshlrev_b32_e32 v118, 16, v211
	v_and_b32_e32 v119, 0xffff0000, v211
	v_pk_fma_f32 v[116:117], v[116:117], v[118:119], v[72:73]
	v_cvt_pk_bf16_f32 v72, v114, v115
	v_cvt_pk_bf16_f32 v73, v116, v117
	v_lshlrev_b32_e32 v114, 16, v66
	v_and_b32_e32 v115, 0xffff0000, v66
	v_lshlrev_b32_e32 v116, 16, v208
	v_and_b32_e32 v117, 0xffff0000, v208
	v_pk_fma_f32 v[110:111], v[110:111], v[116:117], v[114:115]
	v_lshlrev_b32_e32 v66, 16, v67
	v_and_b32_e32 v67, 0xffff0000, v67
	v_lshlrev_b32_e32 v114, 16, v209
	v_and_b32_e32 v115, 0xffff0000, v209
	v_pk_fma_f32 v[112:113], v[112:113], v[114:115], v[66:67]
	v_cvt_pk_bf16_f32 v66, v110, v111
	v_cvt_pk_bf16_f32 v67, v112, v113
	v_lshlrev_b32_e32 v110, 16, v68
	v_and_b32_e32 v111, 0xffff0000, v68
	v_lshlrev_b32_e32 v112, 16, v206
	v_and_b32_e32 v113, 0xffff0000, v206
	v_pk_fma_f32 v[106:107], v[106:107], v[112:113], v[110:111]
	v_lshlrev_b32_e32 v68, 16, v69
	v_and_b32_e32 v69, 0xffff0000, v69
	v_lshlrev_b32_e32 v110, 16, v207
	v_and_b32_e32 v111, 0xffff0000, v207
	v_pk_fma_f32 v[108:109], v[108:109], v[110:111], v[68:69]
	v_cvt_pk_bf16_f32 v68, v106, v107
	v_cvt_pk_bf16_f32 v69, v108, v109
	v_lshlrev_b32_e32 v106, 16, v62
	v_and_b32_e32 v107, 0xffff0000, v62
	v_lshlrev_b32_e32 v108, 16, v204
	v_and_b32_e32 v109, 0xffff0000, v204
	v_pk_fma_f32 v[102:103], v[102:103], v[108:109], v[106:107]
	v_lshlrev_b32_e32 v62, 16, v63
	v_and_b32_e32 v63, 0xffff0000, v63
	v_lshlrev_b32_e32 v106, 16, v205
	v_and_b32_e32 v107, 0xffff0000, v205
	v_pk_fma_f32 v[104:105], v[104:105], v[106:107], v[62:63]
	v_cvt_pk_bf16_f32 v62, v102, v103
	v_cvt_pk_bf16_f32 v63, v104, v105
	v_lshlrev_b32_e32 v102, 16, v64
	v_and_b32_e32 v103, 0xffff0000, v64
	v_lshlrev_b32_e32 v104, 16, v202
	v_and_b32_e32 v105, 0xffff0000, v202
	v_pk_fma_f32 v[98:99], v[98:99], v[104:105], v[102:103]
	v_lshlrev_b32_e32 v64, 16, v65
	v_and_b32_e32 v65, 0xffff0000, v65
	v_lshlrev_b32_e32 v102, 16, v203
	v_and_b32_e32 v103, 0xffff0000, v203
	v_pk_fma_f32 v[100:101], v[100:101], v[102:103], v[64:65]
	v_cvt_pk_bf16_f32 v64, v98, v99
	v_cvt_pk_bf16_f32 v65, v100, v101
	v_lshlrev_b32_e32 v98, 16, v58
	v_and_b32_e32 v99, 0xffff0000, v58
	v_lshlrev_b32_e32 v100, 16, v200
	v_and_b32_e32 v101, 0xffff0000, v200
	v_pk_fma_f32 v[94:95], v[94:95], v[100:101], v[98:99]
	v_lshlrev_b32_e32 v58, 16, v59
	v_and_b32_e32 v59, 0xffff0000, v59
	v_lshlrev_b32_e32 v98, 16, v201
	v_and_b32_e32 v99, 0xffff0000, v201
	v_pk_fma_f32 v[96:97], v[96:97], v[98:99], v[58:59]
	v_cvt_pk_bf16_f32 v58, v94, v95
	v_cvt_pk_bf16_f32 v59, v96, v97
	v_lshlrev_b32_e32 v94, 16, v60
	v_and_b32_e32 v95, 0xffff0000, v60
	v_lshlrev_b32_e32 v96, 16, v198
	v_and_b32_e32 v97, 0xffff0000, v198
	v_pk_fma_f32 v[90:91], v[90:91], v[96:97], v[94:95]
	v_lshlrev_b32_e32 v60, 16, v61
	v_and_b32_e32 v61, 0xffff0000, v61
	v_lshlrev_b32_e32 v94, 16, v199
	v_and_b32_e32 v95, 0xffff0000, v199
	v_pk_fma_f32 v[92:93], v[92:93], v[94:95], v[60:61]
	v_cvt_pk_bf16_f32 v60, v90, v91
	v_cvt_pk_bf16_f32 v61, v92, v93
	v_lshlrev_b32_e32 v90, 16, v54
	v_and_b32_e32 v91, 0xffff0000, v54
	v_lshlrev_b32_e32 v92, 16, v181
	v_and_b32_e32 v93, 0xffff0000, v181
	v_pk_fma_f32 v[86:87], v[86:87], v[92:93], v[90:91]
	v_lshlrev_b32_e32 v54, 16, v55
	v_and_b32_e32 v55, 0xffff0000, v55
	v_lshlrev_b32_e32 v90, 16, v197
	v_and_b32_e32 v91, 0xffff0000, v197
	v_pk_fma_f32 v[88:89], v[88:89], v[90:91], v[54:55]
	v_cvt_pk_bf16_f32 v54, v86, v87
	v_cvt_pk_bf16_f32 v55, v88, v89
	v_lshlrev_b32_e32 v86, 16, v56
	v_and_b32_e32 v87, 0xffff0000, v56
	v_lshlrev_b32_e32 v88, 16, v179
	v_and_b32_e32 v89, 0xffff0000, v179
	v_pk_fma_f32 v[82:83], v[82:83], v[88:89], v[86:87]
	v_lshlrev_b32_e32 v56, 16, v57
	v_and_b32_e32 v57, 0xffff0000, v57
	v_lshlrev_b32_e32 v86, 16, v180
	v_and_b32_e32 v87, 0xffff0000, v180
	v_pk_fma_f32 v[84:85], v[84:85], v[86:87], v[56:57]
	v_cvt_pk_bf16_f32 v56, v82, v83
	v_cvt_pk_bf16_f32 v57, v84, v85
	s_cmp_lg_u32 s55, 5
	s_cbranch_scc1 .LBB0_1076
	s_and_b32 s30, s59, 0x7fffff8
	s_add_i32 s30, s30, s49
	v_lshl_or_b32 v82, s30, 5, v1
	v_readlane_b32 s0, v253, 32
	v_ashrrev_i32_e32 v83, 31, v82
	v_readlane_b32 s1, v253, 33
	s_lshl_b32 s30, s54, 5
	s_and_b32 s30, s30, 0xffffff00
	v_lshl_add_u64 v[82:83], v[82:83], 2, s[0:1]
	global_load_dword v88, v[82:83], off
	global_load_dword v89, v[82:83], off offset:64
	global_load_dword v90, v[82:83], off offset:512
	global_load_dword v91, v[82:83], off offset:576
	v_add_u32_e32 v82, s30, v171
	s_lshl_b32 s30, s54, 7
	s_and_b32 s30, s30, 0x380
	v_ashrrev_i32_e32 v83, 31, v82
	v_readlane_b32 s8, v253, 40
	v_readlane_b32 s9, v253, 41
	v_lshlrev_b64 v[84:85], 11, v[82:83]
	v_or_b32_e32 v83, s30, v178
	v_lshl_add_u64 v[84:85], s[8:9], 0, v[84:85]
	v_lshlrev_b32_e32 v86, 1, v83
	v_mov_b32_e32 v87, v0
	v_lshl_add_u64 v[84:85], v[84:85], 0, v[86:87]
	global_store_dwordx4 v[84:85], v[50:53], off sc1
	global_store_dwordx4 v[84:85], v[78:81], off offset:64 sc1
	s_mov_b64 s[30:31], -1
	v_or_b32_e32 v50, 16, v82
	v_ashrrev_i32_e32 v51, 31, v50
	v_lshlrev_b64 v[50:51], 11, v[50:51]
	v_lshl_add_u64 v[50:51], s[8:9], 0, v[50:51]
	v_lshl_add_u64 v[50:51], v[50:51], 0, v[86:87]
	global_store_dwordx4 v[50:51], v[74:77], off sc1
	global_store_dwordx4 v[50:51], v[70:73], off offset:64 sc1
	v_add_u32_e32 v50, 0x80, v82
	v_ashrrev_i32_e32 v51, 31, v50
	v_lshlrev_b64 v[50:51], 11, v[50:51]
	v_lshl_add_u64 v[50:51], s[8:9], 0, v[50:51]
	v_lshl_add_u64 v[50:51], v[50:51], 0, v[86:87]
	global_store_dwordx4 v[50:51], v[66:69], off sc1
	global_store_dwordx4 v[50:51], v[62:65], off offset:64 sc1
	v_add_u32_e32 v50, 0x90, v82
	v_ashrrev_i32_e32 v51, 31, v50
	v_lshlrev_b64 v[50:51], 11, v[50:51]
	v_lshl_add_u64 v[50:51], s[8:9], 0, v[50:51]
	v_lshl_add_u64 v[50:51], v[50:51], 0, v[86:87]
	global_store_dwordx4 v[50:51], v[58:61], off sc1
	global_store_dwordx4 v[50:51], v[54:57], off offset:64 sc1
	v_mov_b32_e32 v51, 0
	v_mov_b32_e32 v50, v51
	v_mov_b32_e32 v53, v51
	v_mov_b32_e32 v52, v51
	v_mov_b32_e32 v79, v51
	v_mov_b32_e32 v78, v51
	v_mov_b32_e32 v81, v51
	v_mov_b32_e32 v80, v51
	v_mov_b32_e32 v75, v51
	v_mov_b32_e32 v74, v51
	v_mov_b32_e32 v77, v51
	v_mov_b32_e32 v76, v51
	v_mov_b32_e32 v71, v51
	v_mov_b32_e32 v70, v51
	v_mov_b32_e32 v73, v51
	v_mov_b32_e32 v72, v51
	v_mov_b32_e32 v67, v51
	v_mov_b32_e32 v66, v51
	v_mov_b32_e32 v69, v51
	v_mov_b32_e32 v68, v51
	v_mov_b32_e32 v63, v51
	v_mov_b32_e32 v62, v51
	v_mov_b32_e32 v65, v51
	v_mov_b32_e32 v64, v51
	v_mov_b32_e32 v59, v51
	v_mov_b32_e32 v58, v51
	v_mov_b32_e32 v61, v51
	v_mov_b32_e32 v60, v51
	v_mov_b32_e32 v55, v51
	v_mov_b32_e32 v54, v51
	v_mov_b32_e32 v57, v51
	v_mov_b32_e32 v56, v51
	v_readlane_b32 s2, v253, 34
	v_readlane_b32 s3, v253, 35
	v_readlane_b32 s4, v253, 36
	v_readlane_b32 s5, v253, 37
	v_readlane_b32 s6, v253, 38
	v_readlane_b32 s7, v253, 39
	v_readlane_b32 s10, v253, 42
	v_readlane_b32 s11, v253, 43
	v_readlane_b32 s12, v253, 44
	v_readlane_b32 s13, v253, 45
	v_readlane_b32 s14, v253, 46
	v_readlane_b32 s15, v253, 47
	s_waitcnt vmcnt(0)
	v_readlane_b32 s98, v252, 2
	v_readlane_b32 s99, v252, 3
	v_readlane_b32 vcc_lo, v253, 30
	s_lshl_b32 vcc_lo, vcc_lo, 7
	s_lshr_b32 vcc_hi, s54, 3
	s_add_i32 vcc_lo, vcc_lo, vcc_hi
	s_lshl_b32 vcc_lo, vcc_lo, 6
	s_and_b32 vcc_hi, s54, 7
	s_add_i32 vcc_lo, vcc_lo, vcc_hi
	s_lshl_b32 vcc_lo, vcc_lo, 2
	v_mov_b32_e32 v162, vcc_lo
	v_mov_b32_e32 v163, 1
	s_mov_b64 vcc, exec
	s_mov_b64 exec, 1
	s_nop 1
	global_atomic_add v162, v163, s[98:99] offset:4
	s_mov_b64 exec, vcc
	ds_write2_b32 v177, v88, v89 offset1:16
	ds_write2_b32 v177, v90, v91 offset0:128 offset1:144
	s_branch .LBB0_1076

.LBB0_1165:
	s_or_b64 exec, exec, s[0:1]
	v_readlane_b32 s2, v253, 26
	v_readlane_b32 s3, v253, 27
	s_barrier
	s_and_saveexec_b64 s[0:1], s[2:3]
	s_cbranch_execz .LBB0_1169
	s_branch .LBB0_1168

.LBB0_1201:
	s_andn2_b64 vcc, exec, s[14:15]
	s_mov_b64 s[14:15], 0
	s_cbranch_vccnz .LBB0_1205
	v_lshlrev_b32_e32 v114, 16, v236
	v_and_b32_e32 v115, 0xffff0000, v236
	v_lshlrev_b32_e32 v116, 16, v203
	v_and_b32_e32 v117, 0xffff0000, v203
	v_pk_fma_f32 v[110:111], v[110:111], v[116:117], v[114:115]
	v_lshlrev_b32_e32 v114, 16, v235
	v_and_b32_e32 v115, 0xffff0000, v235
	v_lshlrev_b32_e32 v116, 16, v204
	v_and_b32_e32 v117, 0xffff0000, v204
	v_pk_fma_f32 v[112:113], v[112:113], v[116:117], v[114:115]
	v_cvt_pk_bf16_f32 v236, v110, v111
	v_cvt_pk_bf16_f32 v235, v112, v113
	v_lshlrev_b32_e32 v110, 16, v234
	v_and_b32_e32 v111, 0xffff0000, v234
	v_lshlrev_b32_e32 v112, 16, v201
	v_and_b32_e32 v113, 0xffff0000, v201
	v_pk_fma_f32 v[106:107], v[106:107], v[112:113], v[110:111]
	v_lshlrev_b32_e32 v110, 16, v233
	v_and_b32_e32 v111, 0xffff0000, v233
	v_lshlrev_b32_e32 v112, 16, v202
	v_and_b32_e32 v113, 0xffff0000, v202
	v_pk_fma_f32 v[108:109], v[108:109], v[112:113], v[110:111]
	v_cvt_pk_bf16_f32 v234, v106, v107
	v_cvt_pk_bf16_f32 v233, v108, v109
	v_lshlrev_b32_e32 v106, 16, v232
	v_and_b32_e32 v107, 0xffff0000, v232
	v_lshlrev_b32_e32 v108, 16, v199
	v_and_b32_e32 v109, 0xffff0000, v199
	v_pk_fma_f32 v[102:103], v[102:103], v[108:109], v[106:107]
	v_lshlrev_b32_e32 v106, 16, v231
	v_and_b32_e32 v107, 0xffff0000, v231
	v_lshlrev_b32_e32 v108, 16, v200
	v_and_b32_e32 v109, 0xffff0000, v200
	v_pk_fma_f32 v[104:105], v[104:105], v[108:109], v[106:107]
	v_cvt_pk_bf16_f32 v232, v102, v103
	v_cvt_pk_bf16_f32 v231, v104, v105
	v_lshlrev_b32_e32 v102, 16, v230
	v_and_b32_e32 v103, 0xffff0000, v230
	v_lshlrev_b32_e32 v104, 16, v197
	v_and_b32_e32 v105, 0xffff0000, v197
	v_pk_fma_f32 v[98:99], v[98:99], v[104:105], v[102:103]
	v_lshlrev_b32_e32 v102, 16, v229
	v_and_b32_e32 v103, 0xffff0000, v229
	v_lshlrev_b32_e32 v104, 16, v198
	v_and_b32_e32 v105, 0xffff0000, v198
	v_pk_fma_f32 v[100:101], v[100:101], v[104:105], v[102:103]
	v_cvt_pk_bf16_f32 v230, v98, v99
	v_cvt_pk_bf16_f32 v229, v100, v101
	v_lshlrev_b32_e32 v98, 16, v228
	v_and_b32_e32 v99, 0xffff0000, v228
	v_lshlrev_b32_e32 v100, 16, v180
	v_and_b32_e32 v101, 0xffff0000, v180
	v_pk_fma_f32 v[94:95], v[94:95], v[100:101], v[98:99]
	v_lshlrev_b32_e32 v98, 16, v227
	v_and_b32_e32 v99, 0xffff0000, v227
	v_lshlrev_b32_e32 v100, 16, v181
	v_and_b32_e32 v101, 0xffff0000, v181
	v_pk_fma_f32 v[96:97], v[96:97], v[100:101], v[98:99]
	v_cvt_pk_bf16_f32 v228, v94, v95
	v_cvt_pk_bf16_f32 v227, v96, v97
	v_lshlrev_b32_e32 v94, 16, v226
	v_and_b32_e32 v95, 0xffff0000, v226
	v_lshlrev_b32_e32 v96, 16, v178
	v_and_b32_e32 v97, 0xffff0000, v178
	v_pk_fma_f32 v[90:91], v[90:91], v[96:97], v[94:95]
	v_lshlrev_b32_e32 v94, 16, v225
	v_and_b32_e32 v95, 0xffff0000, v225
	v_lshlrev_b32_e32 v96, 16, v179
	v_and_b32_e32 v97, 0xffff0000, v179
	v_pk_fma_f32 v[92:93], v[92:93], v[96:97], v[94:95]
	v_cvt_pk_bf16_f32 v226, v90, v91
	v_cvt_pk_bf16_f32 v225, v92, v93
	v_lshlrev_b32_e32 v90, 16, v224
	v_and_b32_e32 v91, 0xffff0000, v224
	v_lshlrev_b32_e32 v92, 16, v176
	v_and_b32_e32 v93, 0xffff0000, v176
	v_pk_fma_f32 v[86:87], v[86:87], v[92:93], v[90:91]
	v_lshlrev_b32_e32 v90, 16, v223
	v_and_b32_e32 v91, 0xffff0000, v223
	v_lshlrev_b32_e32 v92, 16, v177
	v_and_b32_e32 v93, 0xffff0000, v177
	v_pk_fma_f32 v[88:89], v[88:89], v[92:93], v[90:91]
	v_cvt_pk_bf16_f32 v224, v86, v87
	v_cvt_pk_bf16_f32 v223, v88, v89
	v_lshlrev_b32_e32 v86, 16, v222
	v_and_b32_e32 v87, 0xffff0000, v222
	v_lshlrev_b32_e32 v88, 16, v174
	v_and_b32_e32 v89, 0xffff0000, v174
	v_pk_fma_f32 v[82:83], v[82:83], v[88:89], v[86:87]
	v_lshlrev_b32_e32 v86, 16, v221
	v_and_b32_e32 v87, 0xffff0000, v221
	v_lshlrev_b32_e32 v88, 16, v175
	v_and_b32_e32 v89, 0xffff0000, v175
	v_pk_fma_f32 v[84:85], v[84:85], v[88:89], v[86:87]
	v_cvt_pk_bf16_f32 v222, v82, v83
	v_cvt_pk_bf16_f32 v221, v84, v85
	v_lshlrev_b32_e32 v82, 16, v220
	v_and_b32_e32 v83, 0xffff0000, v220
	v_lshlrev_b32_e32 v84, 16, v172
	v_and_b32_e32 v85, 0xffff0000, v172
	v_pk_fma_f32 v[78:79], v[78:79], v[84:85], v[82:83]
	v_lshlrev_b32_e32 v82, 16, v219
	v_and_b32_e32 v83, 0xffff0000, v219
	v_lshlrev_b32_e32 v84, 16, v173
	v_and_b32_e32 v85, 0xffff0000, v173
	v_pk_fma_f32 v[80:81], v[80:81], v[84:85], v[82:83]
	v_cvt_pk_bf16_f32 v220, v78, v79
	v_cvt_pk_bf16_f32 v219, v80, v81
	v_lshlrev_b32_e32 v78, 16, v218
	v_and_b32_e32 v79, 0xffff0000, v218
	v_lshlrev_b32_e32 v80, 16, v170
	v_and_b32_e32 v81, 0xffff0000, v170
	v_pk_fma_f32 v[74:75], v[74:75], v[80:81], v[78:79]
	v_lshlrev_b32_e32 v78, 16, v217
	v_and_b32_e32 v79, 0xffff0000, v217
	v_lshlrev_b32_e32 v80, 16, v171
	v_and_b32_e32 v81, 0xffff0000, v171
	v_pk_fma_f32 v[76:77], v[76:77], v[80:81], v[78:79]
	v_cvt_pk_bf16_f32 v218, v74, v75
	v_cvt_pk_bf16_f32 v217, v76, v77
	v_lshlrev_b32_e32 v74, 16, v216
	v_and_b32_e32 v75, 0xffff0000, v216
	v_lshlrev_b32_e32 v76, 16, v168
	v_and_b32_e32 v77, 0xffff0000, v168
	v_pk_fma_f32 v[70:71], v[70:71], v[76:77], v[74:75]
	v_lshlrev_b32_e32 v74, 16, v215
	v_and_b32_e32 v75, 0xffff0000, v215
	v_lshlrev_b32_e32 v76, 16, v169
	v_and_b32_e32 v77, 0xffff0000, v169
	v_pk_fma_f32 v[72:73], v[72:73], v[76:77], v[74:75]
	v_cvt_pk_bf16_f32 v216, v70, v71
	v_cvt_pk_bf16_f32 v215, v72, v73
	v_lshlrev_b32_e32 v70, 16, v214
	v_and_b32_e32 v71, 0xffff0000, v214
	v_lshlrev_b32_e32 v72, 16, v166
	v_and_b32_e32 v73, 0xffff0000, v166
	v_pk_fma_f32 v[66:67], v[66:67], v[72:73], v[70:71]
	v_lshlrev_b32_e32 v70, 16, v213
	v_and_b32_e32 v71, 0xffff0000, v213
	v_lshlrev_b32_e32 v72, 16, v167
	v_and_b32_e32 v73, 0xffff0000, v167
	v_pk_fma_f32 v[68:69], v[68:69], v[72:73], v[70:71]
	v_cvt_pk_bf16_f32 v214, v66, v67
	v_cvt_pk_bf16_f32 v213, v68, v69
	v_lshlrev_b32_e32 v66, 16, v212
	v_and_b32_e32 v67, 0xffff0000, v212
	v_lshlrev_b32_e32 v68, 16, v160
	v_and_b32_e32 v69, 0xffff0000, v160
	v_pk_fma_f32 v[62:63], v[62:63], v[68:69], v[66:67]
	v_lshlrev_b32_e32 v66, 16, v211
	v_and_b32_e32 v67, 0xffff0000, v211
	v_lshlrev_b32_e32 v68, 16, v161
	v_and_b32_e32 v69, 0xffff0000, v161
	v_pk_fma_f32 v[64:65], v[64:65], v[68:69], v[66:67]
	v_cvt_pk_bf16_f32 v212, v62, v63
	v_cvt_pk_bf16_f32 v211, v64, v65
	v_lshlrev_b32_e32 v62, 16, v210
	v_and_b32_e32 v63, 0xffff0000, v210
	v_lshlrev_b32_e32 v64, 16, v158
	v_and_b32_e32 v65, 0xffff0000, v158
	v_pk_fma_f32 v[58:59], v[58:59], v[64:65], v[62:63]
	v_lshlrev_b32_e32 v62, 16, v209
	v_and_b32_e32 v63, 0xffff0000, v209
	v_lshlrev_b32_e32 v64, 16, v159
	v_and_b32_e32 v65, 0xffff0000, v159
	v_pk_fma_f32 v[60:61], v[60:61], v[64:65], v[62:63]
	v_cvt_pk_bf16_f32 v210, v58, v59
	v_cvt_pk_bf16_f32 v209, v60, v61
	v_lshlrev_b32_e32 v58, 16, v208
	v_and_b32_e32 v59, 0xffff0000, v208
	v_lshlrev_b32_e32 v60, 16, v156
	v_and_b32_e32 v61, 0xffff0000, v156
	v_pk_fma_f32 v[54:55], v[54:55], v[60:61], v[58:59]
	v_lshlrev_b32_e32 v58, 16, v207
	v_and_b32_e32 v59, 0xffff0000, v207
	v_lshlrev_b32_e32 v60, 16, v157
	v_and_b32_e32 v61, 0xffff0000, v157
	v_pk_fma_f32 v[56:57], v[56:57], v[60:61], v[58:59]
	v_cvt_pk_bf16_f32 v208, v54, v55
	v_cvt_pk_bf16_f32 v207, v56, v57
	v_lshlrev_b32_e32 v54, 16, v206
	v_and_b32_e32 v55, 0xffff0000, v206
	v_lshlrev_b32_e32 v56, 16, v154
	v_and_b32_e32 v57, 0xffff0000, v154
	v_pk_fma_f32 v[50:51], v[50:51], v[56:57], v[54:55]
	v_lshlrev_b32_e32 v54, 16, v205
	v_and_b32_e32 v55, 0xffff0000, v205
	v_lshlrev_b32_e32 v56, 16, v195
	v_and_b32_e32 v57, 0xffff0000, v195
	v_pk_fma_f32 v[52:53], v[52:53], v[56:57], v[54:55]
	v_cvt_pk_bf16_f32 v206, v50, v51
	v_cvt_pk_bf16_f32 v205, v52, v53
	s_cmp_lg_u32 s38, 1
	s_cbranch_scc1 .LBB0_1206
	v_readlane_b32 s98, v252, 2
	v_readlane_b32 s99, v252, 3
	v_readlane_b32 vcc_lo, v253, 30
	s_lshl_b32 vcc_lo, vcc_lo, 7
	s_lshr_b32 vcc_hi, s39, 3
	s_add_i32 vcc_lo, vcc_lo, vcc_hi
	s_lshl_b32 vcc_lo, vcc_lo, 6
	s_and_b32 vcc_hi, s39, 7
	s_add_i32 vcc_lo, vcc_lo, vcc_hi
	s_lshl_b32 vcc_lo, vcc_lo, 2
	v_mov_b32_e32 v162, vcc_lo
.Lm4_poll:
	global_load_dword v163, v162, s[98:99] offset:4 sc1
	s_waitcnt vmcnt(0)
	v_readfirstlane_b32 vcc_lo, v163
	s_nop 3
	s_cmp_ge_u32 vcc_lo, 8
	s_cbranch_scc1 .Lm4_ok
	s_sleep 2
	s_branch .Lm4_poll
.Lm4_ok:
	s_and_b32 s14, s41, 0x7fffff8
	s_add_i32 s14, s14, s18
	v_lshl_or_b32 v50, s14, 5, v1
	v_readlane_b32 s52, v253, 32
	v_ashrrev_i32_e32 v51, 31, v50
	v_readlane_b32 s53, v253, 33
	s_lshl_b32 s14, s39, 5
	s_and_b32 s14, s14, 0xffffff00
	v_lshl_add_u64 v[50:51], v[50:51], 2, s[52:53]
	global_load_dword v88, v[50:51], off
	global_load_dword v89, v[50:51], off offset:64
	global_load_dword v90, v[50:51], off offset:512
	global_load_dword v91, v[50:51], off offset:576
	v_add_u32_e32 v50, s14, v135
	s_lshl_b32 s14, s39, 7
	s_and_b32 s17, s14, 0x380
	s_lshl_b32 s14, s17, 1
	s_add_u32 s14, s22, s14
	v_ashrrev_i32_e32 v51, 31, v50
	s_addc_u32 s15, s23, 0
	v_lshlrev_b64 v[80:81], 11, v[50:51]
	v_lshl_add_u64 v[52:53], s[14:15], 0, v[80:81]
	v_mov_b32_e32 v139, v0
	v_lshl_add_u64 v[52:53], v[52:53], 0, v[138:139]
	global_load_dwordx4 v[92:95], v[52:53], off sc1
	global_load_dwordx4 v[74:77], v[52:53], off offset:64 sc1
	v_or_b32_e32 v52, 16, v50
	v_ashrrev_i32_e32 v53, 31, v52
	v_lshlrev_b64 v[84:85], 11, v[52:53]
	v_lshl_add_u64 v[52:53], s[14:15], 0, v[84:85]
	v_lshl_add_u64 v[52:53], v[52:53], 0, v[138:139]
	global_load_dwordx4 v[70:73], v[52:53], off sc1
	global_load_dwordx4 v[66:69], v[52:53], off offset:64 sc1
	v_add_u32_e32 v52, 0x80, v50
	v_ashrrev_i32_e32 v53, 31, v52
	v_lshlrev_b64 v[82:83], 11, v[52:53]
	v_lshl_add_u64 v[52:53], s[14:15], 0, v[82:83]
	v_lshl_add_u64 v[52:53], v[52:53], 0, v[138:139]
	global_load_dwordx4 v[62:65], v[52:53], off sc1
	global_load_dwordx4 v[58:61], v[52:53], off offset:64 sc1
	v_add_u32_e32 v50, 0x90, v50
	v_ashrrev_i32_e32 v51, 31, v50
	v_lshlrev_b64 v[78:79], 11, v[50:51]
	v_lshl_add_u64 v[50:51], s[14:15], 0, v[78:79]
	v_lshl_add_u64 v[50:51], v[50:51], 0, v[138:139]
	global_load_dwordx4 v[54:57], v[50:51], off sc1
	s_nop 0
	global_load_dwordx4 v[50:53], v[50:51], off offset:64 sc1
	v_readlane_b32 s60, v253, 40
	v_readlane_b32 s61, v253, 41
	v_or_b32_e32 v96, s17, v140
	v_and_b32_e32 v97, 0xffff0000, v236
	v_lshl_add_u64 v[86:87], s[60:61], 0, v[80:81]
	v_lshlrev_b32_e32 v80, 1, v96
	v_lshlrev_b32_e32 v96, 16, v236
	v_mov_b32_e32 v81, v0
	v_lshl_add_u64 v[86:87], v[86:87], 0, v[80:81]
	s_mov_b64 s[14:15], -1
	v_mov_b32_e32 v236, 0
	v_readlane_b32 s54, v253, 34
	v_readlane_b32 s55, v253, 35
	v_readlane_b32 s56, v253, 36
	v_readlane_b32 s57, v253, 37
	v_readlane_b32 s58, v253, 38
	v_readlane_b32 s59, v253, 39
	v_readlane_b32 s62, v253, 42
	v_readlane_b32 s63, v253, 43
	v_readlane_b32 s64, v253, 44
	v_readlane_b32 s65, v253, 45
	v_readlane_b32 s66, v253, 46
	v_readlane_b32 s67, v253, 47
	s_waitcnt vmcnt(0)
	v_lshlrev_b32_e32 v98, 16, v92
	v_and_b32_e32 v99, 0xffff0000, v92
	v_pk_add_f32 v[96:97], v[96:97], v[98:99]
	v_lshlrev_b32_e32 v98, 16, v93
	v_cvt_pk_bf16_f32 v92, v96, v97
	v_lshlrev_b32_e32 v96, 16, v235
	v_and_b32_e32 v97, 0xffff0000, v235
	v_and_b32_e32 v99, 0xffff0000, v93
	v_pk_add_f32 v[96:97], v[96:97], v[98:99]
	v_lshlrev_b32_e32 v98, 16, v94
	v_cvt_pk_bf16_f32 v93, v96, v97
	v_lshlrev_b32_e32 v96, 16, v234
	v_and_b32_e32 v97, 0xffff0000, v234
	v_and_b32_e32 v99, 0xffff0000, v94
	v_pk_add_f32 v[96:97], v[96:97], v[98:99]
	v_lshlrev_b32_e32 v98, 16, v95
	v_cvt_pk_bf16_f32 v94, v96, v97
	v_lshlrev_b32_e32 v96, 16, v233
	v_and_b32_e32 v97, 0xffff0000, v233
	v_and_b32_e32 v99, 0xffff0000, v95
	v_pk_add_f32 v[96:97], v[96:97], v[98:99]
	v_mov_b32_e32 v235, 0
	v_cvt_pk_bf16_f32 v95, v96, v97
	global_store_dwordx4 v[86:87], v[92:95], off
	v_mov_b32_e32 v233, 0
	v_mov_b32_e32 v234, 0
	v_lshlrev_b32_e32 v92, 16, v232
	v_and_b32_e32 v93, 0xffff0000, v232
	v_lshlrev_b32_e32 v94, 16, v74
	v_and_b32_e32 v95, 0xffff0000, v74
	v_pk_add_f32 v[92:93], v[92:93], v[94:95]
	v_lshlrev_b32_e32 v94, 16, v75
	v_cvt_pk_bf16_f32 v74, v92, v93
	v_lshlrev_b32_e32 v92, 16, v231
	v_and_b32_e32 v93, 0xffff0000, v231
	v_and_b32_e32 v95, 0xffff0000, v75
	v_pk_add_f32 v[92:93], v[92:93], v[94:95]
	v_lshlrev_b32_e32 v94, 16, v76
	v_cvt_pk_bf16_f32 v75, v92, v93
	v_lshlrev_b32_e32 v92, 16, v230
	v_and_b32_e32 v93, 0xffff0000, v230
	v_and_b32_e32 v95, 0xffff0000, v76
	v_pk_add_f32 v[92:93], v[92:93], v[94:95]
	v_lshlrev_b32_e32 v94, 16, v77
	v_cvt_pk_bf16_f32 v76, v92, v93
	v_lshlrev_b32_e32 v92, 16, v229
	v_and_b32_e32 v93, 0xffff0000, v229
	v_and_b32_e32 v95, 0xffff0000, v77
	v_pk_add_f32 v[92:93], v[92:93], v[94:95]
	v_mov_b32_e32 v231, 0
	v_cvt_pk_bf16_f32 v77, v92, v93
	global_store_dwordx4 v[86:87], v[74:77], off offset:64
	v_mov_b32_e32 v232, 0
	v_mov_b32_e32 v229, 0
	v_lshl_add_u64 v[74:75], s[60:61], 0, v[84:85]
	v_lshlrev_b32_e32 v76, 16, v228
	v_and_b32_e32 v77, 0xffff0000, v228
	v_lshlrev_b32_e32 v84, 16, v70
	v_and_b32_e32 v85, 0xffff0000, v70
	v_pk_add_f32 v[76:77], v[76:77], v[84:85]
	v_lshlrev_b32_e32 v84, 16, v71
	v_cvt_pk_bf16_f32 v70, v76, v77
	v_lshlrev_b32_e32 v76, 16, v227
	v_and_b32_e32 v77, 0xffff0000, v227
	v_and_b32_e32 v85, 0xffff0000, v71
	v_pk_add_f32 v[76:77], v[76:77], v[84:85]
	v_lshlrev_b32_e32 v84, 16, v72
	v_cvt_pk_bf16_f32 v71, v76, v77
	v_lshlrev_b32_e32 v76, 16, v226
	v_and_b32_e32 v77, 0xffff0000, v226
	v_and_b32_e32 v85, 0xffff0000, v72
	v_pk_add_f32 v[76:77], v[76:77], v[84:85]
	v_lshlrev_b32_e32 v84, 16, v73
	v_cvt_pk_bf16_f32 v72, v76, v77
	v_lshlrev_b32_e32 v76, 16, v225
	v_and_b32_e32 v77, 0xffff0000, v225
	v_and_b32_e32 v85, 0xffff0000, v73
	v_pk_add_f32 v[76:77], v[76:77], v[84:85]
	v_lshl_add_u64 v[74:75], v[74:75], 0, v[80:81]
	v_cvt_pk_bf16_f32 v73, v76, v77
	global_store_dwordx4 v[74:75], v[70:73], off
	v_mov_b32_e32 v230, 0
	v_mov_b32_e32 v227, 0
	v_lshlrev_b32_e32 v70, 16, v224
	v_and_b32_e32 v71, 0xffff0000, v224
	v_lshlrev_b32_e32 v72, 16, v66
	v_and_b32_e32 v73, 0xffff0000, v66
	v_pk_add_f32 v[70:71], v[70:71], v[72:73]
	v_lshlrev_b32_e32 v72, 16, v67
	v_cvt_pk_bf16_f32 v66, v70, v71
	v_lshlrev_b32_e32 v70, 16, v223
	v_and_b32_e32 v71, 0xffff0000, v223
	v_and_b32_e32 v73, 0xffff0000, v67
	v_pk_add_f32 v[70:71], v[70:71], v[72:73]
	v_lshlrev_b32_e32 v72, 16, v68
	v_cvt_pk_bf16_f32 v67, v70, v71
	v_lshlrev_b32_e32 v70, 16, v222
	v_and_b32_e32 v71, 0xffff0000, v222
	v_and_b32_e32 v73, 0xffff0000, v68
	v_pk_add_f32 v[70:71], v[70:71], v[72:73]
	v_lshlrev_b32_e32 v72, 16, v69
	v_cvt_pk_bf16_f32 v68, v70, v71
	v_lshlrev_b32_e32 v70, 16, v221
	v_and_b32_e32 v71, 0xffff0000, v221
	v_and_b32_e32 v73, 0xffff0000, v69
	v_pk_add_f32 v[70:71], v[70:71], v[72:73]
	v_mov_b32_e32 v228, 0
	v_cvt_pk_bf16_f32 v69, v70, v71
	global_store_dwordx4 v[74:75], v[66:69], off offset:64
	v_lshlrev_b32_e32 v70, 16, v62
	v_and_b32_e32 v71, 0xffff0000, v62
	v_lshlrev_b32_e32 v68, 16, v220
	v_and_b32_e32 v69, 0xffff0000, v220
	v_pk_add_f32 v[68:69], v[68:69], v[70:71]
	v_lshlrev_b32_e32 v70, 16, v63
	v_cvt_pk_bf16_f32 v62, v68, v69
	v_lshlrev_b32_e32 v68, 16, v219
	v_and_b32_e32 v69, 0xffff0000, v219
	v_and_b32_e32 v71, 0xffff0000, v63
	v_pk_add_f32 v[68:69], v[68:69], v[70:71]
	v_lshlrev_b32_e32 v70, 16, v64
	v_cvt_pk_bf16_f32 v63, v68, v69
	v_lshlrev_b32_e32 v68, 16, v218
	v_and_b32_e32 v69, 0xffff0000, v218
	v_and_b32_e32 v71, 0xffff0000, v64
	v_pk_add_f32 v[68:69], v[68:69], v[70:71]
	v_lshlrev_b32_e32 v70, 16, v65
	v_cvt_pk_bf16_f32 v64, v68, v69
	v_lshlrev_b32_e32 v68, 16, v217
	v_and_b32_e32 v69, 0xffff0000, v217
	v_and_b32_e32 v71, 0xffff0000, v65
	v_lshl_add_u64 v[66:67], s[60:61], 0, v[82:83]
	v_pk_add_f32 v[68:69], v[68:69], v[70:71]
	v_lshl_add_u64 v[66:67], v[66:67], 0, v[80:81]
	v_cvt_pk_bf16_f32 v65, v68, v69
	global_store_dwordx4 v[66:67], v[62:65], off
	v_mov_b32_e32 v225, 0
	v_mov_b32_e32 v226, 0
	v_lshlrev_b32_e32 v62, 16, v216
	v_and_b32_e32 v63, 0xffff0000, v216
	v_lshlrev_b32_e32 v64, 16, v58
	v_and_b32_e32 v65, 0xffff0000, v58
	v_pk_add_f32 v[62:63], v[62:63], v[64:65]
	v_lshlrev_b32_e32 v64, 16, v59
	v_cvt_pk_bf16_f32 v58, v62, v63
	v_lshlrev_b32_e32 v62, 16, v215
	v_and_b32_e32 v63, 0xffff0000, v215
	v_and_b32_e32 v65, 0xffff0000, v59
	v_pk_add_f32 v[62:63], v[62:63], v[64:65]
	v_lshlrev_b32_e32 v64, 16, v60
	v_cvt_pk_bf16_f32 v59, v62, v63
	v_lshlrev_b32_e32 v62, 16, v214
	v_and_b32_e32 v63, 0xffff0000, v214
	v_and_b32_e32 v65, 0xffff0000, v60
	v_pk_add_f32 v[62:63], v[62:63], v[64:65]
	v_lshlrev_b32_e32 v64, 16, v61
	v_cvt_pk_bf16_f32 v60, v62, v63
	v_lshlrev_b32_e32 v62, 16, v213
	v_and_b32_e32 v63, 0xffff0000, v213
	v_and_b32_e32 v65, 0xffff0000, v61
	v_pk_add_f32 v[62:63], v[62:63], v[64:65]
	v_mov_b32_e32 v223, 0
	v_cvt_pk_bf16_f32 v61, v62, v63
	global_store_dwordx4 v[66:67], v[58:61], off offset:64
	v_lshlrev_b32_e32 v62, 16, v54
	v_and_b32_e32 v63, 0xffff0000, v54
	v_lshlrev_b32_e32 v60, 16, v212
	v_and_b32_e32 v61, 0xffff0000, v212
	v_pk_add_f32 v[60:61], v[60:61], v[62:63]
	v_lshlrev_b32_e32 v62, 16, v55
	v_cvt_pk_bf16_f32 v54, v60, v61
	v_lshlrev_b32_e32 v60, 16, v211
	v_and_b32_e32 v61, 0xffff0000, v211
	v_and_b32_e32 v63, 0xffff0000, v55
	v_pk_add_f32 v[60:61], v[60:61], v[62:63]
	v_lshlrev_b32_e32 v62, 16, v56
	v_cvt_pk_bf16_f32 v55, v60, v61
	v_lshlrev_b32_e32 v60, 16, v210
	v_and_b32_e32 v61, 0xffff0000, v210
	v_and_b32_e32 v63, 0xffff0000, v56
	v_pk_add_f32 v[60:61], v[60:61], v[62:63]
	v_lshlrev_b32_e32 v62, 16, v57
	v_cvt_pk_bf16_f32 v56, v60, v61
	v_lshlrev_b32_e32 v60, 16, v209
	v_and_b32_e32 v61, 0xffff0000, v209
	v_and_b32_e32 v63, 0xffff0000, v57
	v_lshl_add_u64 v[58:59], s[60:61], 0, v[78:79]
	v_pk_add_f32 v[60:61], v[60:61], v[62:63]
	v_lshl_add_u64 v[58:59], v[58:59], 0, v[80:81]
	v_cvt_pk_bf16_f32 v57, v60, v61
	global_store_dwordx4 v[58:59], v[54:57], off
	v_mov_b32_e32 v224, 0
	v_mov_b32_e32 v221, 0
	v_lshlrev_b32_e32 v54, 16, v208
	v_and_b32_e32 v55, 0xffff0000, v208
	v_lshlrev_b32_e32 v56, 16, v50
	v_and_b32_e32 v57, 0xffff0000, v50
	v_pk_add_f32 v[54:55], v[54:55], v[56:57]
	v_lshlrev_b32_e32 v56, 16, v51
	v_cvt_pk_bf16_f32 v50, v54, v55
	v_lshlrev_b32_e32 v54, 16, v207
	v_and_b32_e32 v55, 0xffff0000, v207
	v_and_b32_e32 v57, 0xffff0000, v51
	v_pk_add_f32 v[54:55], v[54:55], v[56:57]
	v_lshlrev_b32_e32 v56, 16, v52
	v_cvt_pk_bf16_f32 v51, v54, v55
	v_lshlrev_b32_e32 v54, 16, v206
	v_and_b32_e32 v55, 0xffff0000, v206
	v_and_b32_e32 v57, 0xffff0000, v52
	v_pk_add_f32 v[54:55], v[54:55], v[56:57]
	v_lshlrev_b32_e32 v56, 16, v53
	v_cvt_pk_bf16_f32 v52, v54, v55
	v_lshlrev_b32_e32 v54, 16, v205
	v_and_b32_e32 v55, 0xffff0000, v205
	v_and_b32_e32 v57, 0xffff0000, v53
	v_pk_add_f32 v[54:55], v[54:55], v[56:57]
	v_mov_b32_e32 v222, 0
	v_cvt_pk_bf16_f32 v53, v54, v55
	v_mov_b32_e32 v219, 0
	v_mov_b32_e32 v220, 0
	v_mov_b32_e32 v217, 0
	v_mov_b32_e32 v218, 0
	v_mov_b32_e32 v215, 0
	v_mov_b32_e32 v216, 0
	v_mov_b32_e32 v213, 0
	v_mov_b32_e32 v214, 0
	v_mov_b32_e32 v211, 0
	v_mov_b32_e32 v212, 0
	v_mov_b32_e32 v209, 0
	v_mov_b32_e32 v210, 0
	v_mov_b32_e32 v207, 0
	v_mov_b32_e32 v208, 0
	v_mov_b32_e32 v205, 0
	v_mov_b32_e32 v206, 0
	global_store_dwordx4 v[58:59], v[50:53], off offset:64
	ds_write2_b32 v137, v88, v89 offset1:16
	ds_write2_b32 v137, v90, v91 offset0:128 offset1:144
	s_branch .LBB0_1206
